# far-tile softmax: rescale test on the reference values, exp2 only when rescaling; running sum without add-of-zero
# baseline (speedup 1.0000x reference)
.LBB0_1107:
	s_lshl_b32 s2, 1, s10
	v_and_b32_e32 v0, s2, v205
	v_cmp_ne_u32_e32 vcc, 0, v0
	s_or_b64 s[2:3], s[8:9], vcc
	v_cndmask_b32_e64 v0, 0, 1, s[2:3]
	v_cmp_ne_u32_e32 vcc, 0, v0
	s_cbranch_vccz .LBB0_1118
	s_lshl_b32 s24, s10, 6
	s_cmp_gt_i32 s24, s17
	s_cselect_b64 s[10:11], -1, 0
	s_cmp_eq_u32 s23, 2
	s_cselect_b64 s[12:13], -1, 0
	s_sub_i32 s5, s20, s24
	s_cmpk_gt_i32 s5, 0x1ff
	s_cselect_b64 s[26:27], -1, 0
	s_lshl_b32 s5, s21, 14
	v_add_u32_e32 v32, s5, v206
	ds_read_b128 v[0:3], v32
	ds_read_b128 v[4:7], v32 offset:512
	ds_read_b128 v[8:11], v32 offset:2048
	ds_read_b128 v[12:15], v32 offset:2560
	ds_read_b128 v[16:19], v32 offset:4096
	ds_read_b128 v[20:23], v32 offset:4608
	ds_read_b128 v[24:27], v32 offset:6144
	ds_read_b128 v[28:31], v32 offset:6656
	s_waitcnt lgkmcnt(0)
	v_mfma_f32_32x32x16_bf16 v[114:129], v[0:3], v[130:133], 0
	s_and_b64 s[12:13], s[12:13], s[26:27]
	s_or_b64 s[10:11], s[10:11], s[12:13]
	s_mov_b64 s[12:13], -1
	s_andn2_b64 vcc, exec, s[10:11]
	v_mfma_f32_32x32x16_bf16 v[98:113], v[4:7], v[130:133], 0
	ds_read_b128 v[0:3], v32 offset:8192
	ds_read_b128 v[4:7], v32 offset:8704
	v_mfma_f32_32x32x16_bf16 v[114:129], v[8:11], v[134:137], v[114:129]
	v_mfma_f32_32x32x16_bf16 v[98:113], v[12:15], v[134:137], v[98:113]
	ds_read_b128 v[8:11], v32 offset:10240
	ds_read_b128 v[12:15], v32 offset:10752
	v_mfma_f32_32x32x16_bf16 v[114:129], v[16:19], v[138:141], v[114:129]
	v_mfma_f32_32x32x16_bf16 v[98:113], v[20:23], v[138:141], v[98:113]
	ds_read_b128 v[16:19], v32 offset:12288
	ds_read_b128 v[20:23], v32 offset:12800
	v_mfma_f32_32x32x16_bf16 v[114:129], v[24:27], v[142:145], v[114:129]
	v_mfma_f32_32x32x16_bf16 v[98:113], v[28:31], v[142:145], v[98:113]
	ds_read_b128 v[24:27], v32 offset:14336
	ds_read_b128 v[28:31], v32 offset:14848
	s_waitcnt lgkmcnt(0)
	v_mfma_f32_32x32x16_bf16 v[114:129], v[0:3], v[146:149], v[114:129]
	v_mfma_f32_32x32x16_bf16 v[98:113], v[4:7], v[146:149], v[98:113]
	v_mfma_f32_32x32x16_bf16 v[114:129], v[8:11], v[150:153], v[114:129]
	v_mfma_f32_32x32x16_bf16 v[98:113], v[12:15], v[150:153], v[98:113]
	v_mfma_f32_32x32x16_bf16 v[114:129], v[16:19], v[154:157], v[114:129]
	v_mfma_f32_32x32x16_bf16 v[98:113], v[20:23], v[154:157], v[98:113]
	v_mfma_f32_32x32x16_bf16 v[114:129], v[24:27], v[158:161], v[114:129]
	v_mfma_f32_32x32x16_bf16 v[98:113], v[28:31], v[158:161], v[98:113]
	s_cbranch_vccz .LBB0_1116
	s_nop 9
	v_max3_f32 v0, v114, s94, v115
	v_max3_f32 v0, v0, v116, v117
	v_max3_f32 v0, v0, v118, v119
	v_max3_f32 v0, v0, v120, v121
	v_max3_f32 v0, v0, v122, v123
	v_max3_f32 v0, v0, v124, v125
	v_max3_f32 v0, v0, v126, v127
	v_max3_f32 v0, v0, v128, v129
	v_max3_f32 v0, v0, v98, v99
	v_max3_f32 v0, v0, v100, v101
	v_max3_f32 v0, v0, v102, v103
	v_max3_f32 v0, v0, v104, v105
	v_max3_f32 v0, v0, v106, v107
	v_max3_f32 v0, v0, v108, v109
	v_max3_f32 v0, v0, v110, v111
	v_max3_f32 v0, v0, v112, v113
	ds_bpermute_b32 v1, v168, v0
	v_cndmask_b32_e64 v2, v233, v204, s[2:3]
	v_max_f32_e32 v3, v209, v209
	s_waitcnt lgkmcnt(0)
	v_max_f32_e32 v1, v1, v1
	v_max_f32_e32 v0, v0, v1
	v_add_f32_e32 v0, v2, v0
	v_max_f32_e32 v210, v3, v0
	v_sub_f32_e32 v1, v210, v3
	v_cmp_lt_f32_e32 vcc, 0x41c00000, v1
	v_cndmask_b32_e32 v210, v3, v210, vcc
	v_sub_f32_e32 v167, v2, v210
	v_add_f32_e32 v0, v114, v167
	v_add_f32_e32 v1, v115, v167
	v_exp_f32_e32 v0, v0
	v_exp_f32_e32 v1, v1
	v_add_f32_e32 v2, v116, v167
	v_exp_f32_e32 v2, v2
	v_add_f32_e32 v3, v117, v167
	v_exp_f32_e32 v3, v3
	v_add_f32_e32 v4, v1, v0
	v_add_f32_e32 v4, v2, v4
	v_add_f32_e32 v8, v3, v4
	v_add_f32_e32 v4, v118, v167
	v_exp_f32_e32 v4, v4
	v_add_f32_e32 v5, v119, v167
	v_exp_f32_e32 v5, v5
	v_add_f32_e32 v6, v120, v167
	v_exp_f32_e32 v6, v6
	v_add_f32_e32 v7, v121, v167
	v_exp_f32_e32 v7, v7
	v_add_f32_e32 v8, v4, v8
	v_add_f32_e32 v8, v5, v8
	v_add_f32_e32 v8, v6, v8
	v_add_f32_e32 v12, v7, v8
	v_add_f32_e32 v8, v122, v167
	v_exp_f32_e32 v8, v8
	v_add_f32_e32 v9, v123, v167
	v_exp_f32_e32 v9, v9
	v_add_f32_e32 v10, v124, v167
	v_exp_f32_e32 v10, v10
	v_add_f32_e32 v11, v125, v167
	v_exp_f32_e32 v11, v11
	v_add_f32_e32 v12, v8, v12
	v_add_f32_e32 v12, v9, v12
	v_add_f32_e32 v12, v10, v12
	v_add_f32_e32 v16, v11, v12
	v_add_f32_e32 v12, v126, v167
	v_exp_f32_e32 v12, v12
	v_add_f32_e32 v13, v127, v167
	v_exp_f32_e32 v13, v13
	v_add_f32_e32 v14, v128, v167
	v_exp_f32_e32 v14, v14
	v_add_f32_e32 v15, v129, v167
	v_exp_f32_e32 v15, v15
	v_add_f32_e32 v16, v12, v16
	v_add_f32_e32 v16, v13, v16
	v_add_f32_e32 v16, v14, v16
	v_add_f32_e32 v20, v15, v16
	v_add_f32_e32 v16, v98, v167
	v_exp_f32_e32 v16, v16
	v_add_f32_e32 v17, v99, v167
	v_exp_f32_e32 v17, v17
	v_add_f32_e32 v18, v100, v167
	v_exp_f32_e32 v18, v18
	v_add_f32_e32 v19, v101, v167
	v_exp_f32_e32 v19, v19
	v_add_f32_e32 v20, v16, v20
	v_add_f32_e32 v20, v17, v20
	v_add_f32_e32 v20, v18, v20
	v_add_f32_e32 v24, v19, v20
	v_add_f32_e32 v20, v102, v167
	v_exp_f32_e32 v20, v20
	v_add_f32_e32 v21, v103, v167
	v_exp_f32_e32 v21, v21
	v_add_f32_e32 v22, v104, v167
	v_exp_f32_e32 v22, v22
	v_add_f32_e32 v23, v105, v167
	v_exp_f32_e32 v23, v23
	v_add_f32_e32 v24, v20, v24
	v_add_f32_e32 v24, v21, v24
	v_add_f32_e32 v24, v22, v24
	v_add_f32_e32 v28, v23, v24
	v_add_f32_e32 v24, v106, v167
	v_exp_f32_e32 v24, v24
	v_add_f32_e32 v25, v107, v167
	v_exp_f32_e32 v25, v25
	v_add_f32_e32 v26, v108, v167
	v_exp_f32_e32 v26, v26
	v_add_f32_e32 v27, v109, v167
	v_exp_f32_e32 v27, v27
	v_add_f32_e32 v28, v24, v28
	v_add_f32_e32 v28, v25, v28
	v_add_f32_e32 v28, v26, v28
	v_add_f32_e32 v31, v27, v28
	v_add_f32_e32 v28, v110, v167
	v_exp_f32_e32 v28, v28
	v_add_f32_e32 v29, v111, v167
	v_exp_f32_e32 v29, v29
	v_add_f32_e32 v30, v112, v167
	v_exp_f32_e32 v30, v30
	v_add_f32_e32 v31, v28, v31
	v_add_f32_e32 v166, v29, v31
	v_mov_b32_e32 v31, v113
	v_pk_add_f32 v[166:167], v[30:31], v[166:167]
	s_cbranch_execz .LBB0_1117
.LBB0_1110:
	v_cmp_neq_f32_e32 vcc, v209, v210
	v_mov_b32_e32 v32, 1.0
	s_cbranch_vccz .LBB0_1112
	v_sub_f32_e32 v31, v209, v210
	v_exp_f32_e32 v32, v31
	s_nop 0
